# v29 + streaming nt hint on the final f32 output stores (fused P12 epilogue) and on the w2 tail-conversion stores of P1/P11
# baseline (speedup 1.0000x reference)
; #define LAS __attribute__((address_space(3)))
; template <bool GAIN = false>
; __device__ __forceinline__ void tr_super(const float* W, size_t ldw, int k0, int c0, bf16* WT, int nd0, int K, LAS unsigned char* lds, int wave, int lane, int kd0, const float* gk = nullptr) {
;     LAS float* tile = (LAS float*)lds;
; #pragma unroll
;     for (int r = 0; r < 8; ++r)
; #pragma unroll
;         for (int h = 0; h < 8; ++h) tile[(8 * wave + r) * 513 + 64 * h + lane] = __builtin_nontemporal_load(W + (size_t)(k0 + 8 * wave + r) * ldw + c0 + 64 * h + lane);
;     __syncthreads();
; __device__ __forceinline__ void cv_tail_w2(const float* W, bf16* WT, unsigned* head, LAS unsigned char* lds, int wave, int lane) {
;     ...
;     volatile LAS unsigned* slot = (volatile LAS unsigned*)(lds + 139264);
;     for (;;) {
;         if (wave == 0 && lane == 0) *slot = __hip_atomic_fetch_add(head, 1u, __ATOMIC_RELAXED, __HIP_MEMORY_SCOPE_AGENT);
;         __syncthreads();
;         const unsigned o = (unsigned)__builtin_amdgcn_readfirstlane((int)*slot);
;         if (o >= (unsigned)N) break;
;         tr_super(W, D, 64 * (int)(o >> 3), 512 * (int)(o & 7), WT, 512 * (int)(o & 7), FF, lds, wave, lane, 64 * (int)(o >> 3));
.LBB0_128:
	s_or_b64 exec, exec, s[14:15]
	s_waitcnt lgkmcnt(0)
	s_barrier
	ds_read_b32 v37, v2
	s_mov_b64 s[14:15], -1
	s_waitcnt lgkmcnt(0)
	v_readfirstlane_b32 s16, v37
	s_cmpk_gt_u32 s16, 0x55f
	s_cbranch_scc1 .LBB0_123
	s_lshl_b32 s10, s16, 9
	s_and_b32 s17, s10, 0xe00
	s_and_b32 s10, s16, 0x7f8
	s_add_i32 s10, s10, s61
	s_lshl_b32 s14, s10, 3
	s_lshl_b32 s10, s17, 2
	s_mov_b32 s15, s11
	v_lshl_add_u64 v[38:39], v[4:5], 0, s[10:11]
	s_lshl_b64 s[18:19], s[14:15], 14
	s_or_b32 s10, s14, 1
	v_lshl_add_u64 v[40:41], v[38:39], 0, s[18:19]
	s_lshl_b64 s[18:19], s[10:11], 14
	s_or_b32 s10, s14, 2
	global_load_dword v37, v[40:41], off nt
	global_load_dword v42, v[40:41], off offset:256 nt
	global_load_dword v43, v[40:41], off offset:512 nt
	global_load_dword v44, v[40:41], off offset:768 nt
	global_load_dword v45, v[40:41], off offset:1024 nt
	global_load_dword v46, v[40:41], off offset:1280 nt
	global_load_dword v47, v[40:41], off offset:1536 nt
	global_load_dword v48, v[40:41], off offset:1792 nt
	v_lshl_add_u64 v[40:41], v[38:39], 0, s[18:19]
	s_lshl_b64 s[18:19], s[10:11], 14
	s_or_b32 s10, s14, 3
	global_load_dword v49, v[40:41], off nt
	global_load_dword v50, v[40:41], off offset:256 nt
	global_load_dword v51, v[40:41], off offset:512 nt
	global_load_dword v52, v[40:41], off offset:768 nt
	global_load_dword v53, v[40:41], off offset:1024 nt
	global_load_dword v54, v[40:41], off offset:1280 nt
	global_load_dword v55, v[40:41], off offset:1536 nt
	global_load_dword v56, v[40:41], off offset:1792 nt
	v_lshl_add_u64 v[40:41], v[38:39], 0, s[18:19]
	s_lshl_b64 s[18:19], s[10:11], 14
	s_or_b32 s10, s14, 4
	global_load_dword v57, v[40:41], off nt
	global_load_dword v58, v[40:41], off offset:256 nt
	global_load_dword v59, v[40:41], off offset:512 nt
	global_load_dword v60, v[40:41], off offset:768 nt
	global_load_dword v61, v[40:41], off offset:1024 nt
	global_load_dword v62, v[40:41], off offset:1280 nt
	global_load_dword v63, v[40:41], off offset:1536 nt
	global_load_dword v64, v[40:41], off offset:1792 nt
	v_lshl_add_u64 v[40:41], v[38:39], 0, s[18:19]
	s_lshl_b64 s[18:19], s[10:11], 14
	s_or_b32 s10, s14, 5
	global_load_dword v65, v[40:41], off nt
	global_load_dword v66, v[40:41], off offset:256 nt
	global_load_dword v67, v[40:41], off offset:512 nt
	global_load_dword v68, v[40:41], off offset:768 nt
	global_load_dword v69, v[40:41], off offset:1024 nt
	global_load_dword v70, v[40:41], off offset:1280 nt
	global_load_dword v71, v[40:41], off offset:1536 nt
	global_load_dword v72, v[40:41], off offset:1792 nt
	v_lshl_add_u64 v[40:41], v[38:39], 0, s[18:19]
	s_lshl_b64 s[18:19], s[10:11], 14
	s_or_b32 s10, s14, 6
	global_load_dword v73, v[40:41], off nt
	global_load_dword v74, v[40:41], off offset:256 nt
	global_load_dword v75, v[40:41], off offset:512 nt
	global_load_dword v76, v[40:41], off offset:768 nt
	global_load_dword v77, v[40:41], off offset:1024 nt
	global_load_dword v78, v[40:41], off offset:1280 nt
	global_load_dword v79, v[40:41], off offset:1536 nt
	global_load_dword v80, v[40:41], off offset:1792 nt
	v_lshl_add_u64 v[40:41], v[38:39], 0, s[18:19]
	s_lshl_b64 s[18:19], s[10:11], 14
	s_or_b32 s10, s14, 7
	s_lshl_b64 s[14:15], s[10:11], 14
	global_load_dword v81, v[40:41], off nt
	global_load_dword v82, v[40:41], off offset:256 nt
	global_load_dword v83, v[40:41], off offset:512 nt
	global_load_dword v84, v[40:41], off offset:768 nt
	global_load_dword v85, v[40:41], off offset:1024 nt
	global_load_dword v86, v[40:41], off offset:1280 nt
	global_load_dword v87, v[40:41], off offset:1536 nt
	global_load_dword v88, v[40:41], off offset:1792 nt
	v_lshl_add_u64 v[40:41], v[38:39], 0, s[18:19]
	v_lshl_add_u64 v[38:39], v[38:39], 0, s[14:15]
	global_load_dword v89, v[40:41], off nt
	global_load_dword v90, v[40:41], off offset:256 nt
	global_load_dword v91, v[40:41], off offset:512 nt
	global_load_dword v92, v[40:41], off offset:768 nt
	global_load_dword v93, v[40:41], off offset:1024 nt
	global_load_dword v94, v[40:41], off offset:1280 nt
	global_load_dword v95, v[40:41], off offset:1536 nt
	s_nop 0
	global_load_dword v40, v[40:41], off offset:1792 nt
	s_nop 0
	global_load_dword v41, v[38:39], off nt
	global_load_dword v96, v[38:39], off offset:256 nt
	global_load_dword v97, v[38:39], off offset:512 nt
	global_load_dword v98, v[38:39], off offset:768 nt
	global_load_dword v99, v[38:39], off offset:1024 nt
	global_load_dword v100, v[38:39], off offset:1280 nt
	global_load_dword v101, v[38:39], off offset:1536 nt
	s_nop 0
	global_load_dword v38, v[38:39], off offset:1792 nt
	s_add_i32 s17, s17, s3
	s_ashr_i32 s14, s17, 8
	s_lshr_b32 s10, s16, 3
	s_mulk_i32 s14, 0xac
	s_add_i32 s14, s14, s10
	s_ashr_i32 s15, s14, 31
	s_lshl_b64 s[14:15], s[14:15], 15
	s_waitcnt vmcnt(62)
	ds_write2st64_b32 v1, v37, v42 offset1:1
	s_waitcnt vmcnt(60)
	ds_write2st64_b32 v1, v43, v44 offset0:2 offset1:3
	s_waitcnt vmcnt(58)
	ds_write2st64_b32 v1, v45, v46 offset0:4 offset1:5
	s_waitcnt vmcnt(56)
	ds_write2st64_b32 v1, v47, v48 offset0:6 offset1:7
	s_waitcnt vmcnt(54)
	ds_write2st64_b32 v23, v49, v50 offset0:8 offset1:9
	s_waitcnt vmcnt(52)
	ds_write2st64_b32 v23, v51, v52 offset0:10 offset1:11
	s_waitcnt vmcnt(50)
	ds_write2st64_b32 v23, v53, v54 offset0:12 offset1:13
	s_waitcnt vmcnt(48)
	ds_write2st64_b32 v23, v55, v56 offset0:14 offset1:15
	s_waitcnt vmcnt(46)
	ds_write2st64_b32 v24, v57, v58 offset0:16 offset1:17
	s_waitcnt vmcnt(44)
	ds_write2st64_b32 v24, v59, v60 offset0:18 offset1:19
	s_waitcnt vmcnt(42)
; #define LAS __attribute__((address_space(3)))
; __host__ __device__ __forceinline__ size_t blk(int r, int k, int K) { return (((size_t)((r >> 8) * (K >> 6) + (k >> 6))) << 14) + (size_t)(((r & 255) << 6) + (k & 63)); }
; __device__ __forceinline__ unsigned pk2(float lo, float hi) { f32x2 v = {lo, hi}; bf16x2_t b = __builtin_convertvector(v, bf16x2_t); return __builtin_bit_cast(unsigned, b); }
; template <bool GAIN = false>
; __device__ __forceinline__ void tr_super(const float* W, size_t ldw, int k0, int c0, bf16* WT, int nd0, int K, LAS unsigned char* lds, int wave, int lane, int kd0, const float* gk = nullptr) {
;     ...
;     const int c = lane & 7;
;     f32x4 g0 = {1.f, 1.f, 1.f, 1.f}, g1 = g0;
;     if (GAIN) { g0 = *(const f32x4*)(gk + k0 + 8 * c); g1 = *(const f32x4*)(gk + k0 + 8 * c + 4); }
; #pragma unroll
;     for (int j = 0; j < 8; ++j) { const int n = (lane >> 3) + 8 * j; const LAS float* t = tile + (8 * c) * 513 + 64 * wave + n;
;         u32x4 o; o.x = pk2(t[0 * 513] * g0.x, t[1 * 513] * g0.y); o.y = pk2(t[2 * 513] * g0.z, t[3 * 513] * g0.w); o.z = pk2(t[4 * 513] * g1.x, t[5 * 513] * g1.y); o.w = pk2(t[6 * 513] * g1.z, t[7 * 513] * g1.w);
;         *(u32x4*)(WT + blk(nd0 + 64 * wave + n, kd0 + 8 * c, K)) = o; }
;     __syncthreads();
	ds_write2st64_b32 v24, v61, v62 offset0:20 offset1:21
	s_waitcnt vmcnt(40)
	ds_write2st64_b32 v24, v63, v64 offset0:22 offset1:23
	s_waitcnt vmcnt(38)
	ds_write2st64_b32 v25, v65, v66 offset0:24 offset1:25
	s_waitcnt vmcnt(36)
	ds_write2st64_b32 v25, v67, v68 offset0:26 offset1:27
	s_waitcnt vmcnt(34)
	ds_write2st64_b32 v25, v69, v70 offset0:28 offset1:29
	s_waitcnt vmcnt(32)
	ds_write2st64_b32 v25, v71, v72 offset0:30 offset1:31
	s_waitcnt vmcnt(30)
	ds_write2st64_b32 v26, v73, v74 offset0:32 offset1:33
	s_waitcnt vmcnt(28)
	ds_write2st64_b32 v26, v75, v76 offset0:34 offset1:35
	s_waitcnt vmcnt(26)
	ds_write2st64_b32 v26, v77, v78 offset0:36 offset1:37
	s_waitcnt vmcnt(24)
	ds_write2st64_b32 v26, v79, v80 offset0:38 offset1:39
	s_waitcnt vmcnt(22)
	ds_write2st64_b32 v27, v81, v82 offset0:40 offset1:41
	s_waitcnt vmcnt(20)
	ds_write2st64_b32 v27, v83, v84 offset0:42 offset1:43
	s_waitcnt vmcnt(18)
	ds_write2st64_b32 v27, v85, v86 offset0:44 offset1:45
	s_waitcnt vmcnt(16)
	ds_write2st64_b32 v27, v87, v88 offset0:46 offset1:47
	s_waitcnt vmcnt(14)
	ds_write2st64_b32 v28, v89, v90 offset0:48 offset1:49
	s_waitcnt vmcnt(12)
	ds_write2st64_b32 v28, v91, v92 offset0:50 offset1:51
	s_waitcnt vmcnt(10)
	ds_write2st64_b32 v28, v93, v94 offset0:52 offset1:53
	s_waitcnt vmcnt(8)
	ds_write2st64_b32 v28, v95, v40 offset0:54 offset1:55
	s_waitcnt vmcnt(6)
	ds_write2st64_b32 v29, v41, v96 offset0:56 offset1:57
	s_waitcnt vmcnt(4)
	ds_write2st64_b32 v29, v97, v98 offset0:58 offset1:59
	s_waitcnt vmcnt(2)
	ds_write2st64_b32 v29, v99, v100 offset0:60 offset1:61
	s_waitcnt vmcnt(0)
	ds_write2st64_b32 v29, v101, v38 offset0:62 offset1:63
	s_waitcnt lgkmcnt(0)
	s_barrier
	ds_read2_b32 v[42:43], v30 offset0:1 offset1:9
	ds_read2_b32 v[44:45], v22 offset1:8
	ds_read2_b32 v[46:47], v31 offset0:2 offset1:10
	ds_read2_b32 v[48:49], v32 offset0:3 offset1:11
	ds_read2_b32 v[50:51], v33 offset0:4 offset1:12
	ds_read2_b32 v[52:53], v34 offset0:5 offset1:13
	ds_read2_b32 v[54:55], v35 offset0:6 offset1:14
	ds_read2_b32 v[56:57], v36 offset0:7 offset1:15
	s_waitcnt lgkmcnt(6)
	v_cvt_pk_bf16_f32 v38, v44, v42
	s_waitcnt lgkmcnt(4)
	v_cvt_pk_bf16_f32 v39, v46, v48
	s_waitcnt lgkmcnt(2)
	v_cvt_pk_bf16_f32 v40, v50, v52
	v_lshl_add_u64 v[58:59], v[6:7], 0, s[14:15]
	s_waitcnt lgkmcnt(0)
	v_cvt_pk_bf16_f32 v41, v54, v56
	global_store_dwordx4 v[58:59], v[38:41], off nt
	s_nop 1
	v_cvt_pk_bf16_f32 v38, v45, v43
	v_cvt_pk_bf16_f32 v39, v47, v49
	v_cvt_pk_bf16_f32 v40, v51, v53
	v_cvt_pk_bf16_f32 v41, v55, v57
	ds_read2_b32 v[44:45], v22 offset0:16 offset1:24
	ds_read2_b32 v[46:47], v30 offset0:17 offset1:25
	ds_read2_b32 v[48:49], v31 offset0:18 offset1:26
	ds_read2_b32 v[50:51], v32 offset0:19 offset1:27
	ds_read2_b32 v[52:53], v33 offset0:20 offset1:28
	ds_read2_b32 v[54:55], v34 offset0:21 offset1:29
	ds_read2_b32 v[56:57], v35 offset0:22 offset1:30
	ds_read2_b32 v[58:59], v36 offset0:23 offset1:31
	v_lshl_add_u64 v[42:43], v[8:9], 0, s[14:15]
	global_store_dwordx4 v[42:43], v[38:41], off nt
	v_lshl_add_u64 v[42:43], v[10:11], 0, s[14:15]
	s_waitcnt lgkmcnt(6)
	v_cvt_pk_bf16_f32 v38, v44, v46
	s_waitcnt lgkmcnt(4)
	v_cvt_pk_bf16_f32 v39, v48, v50
	s_waitcnt lgkmcnt(2)
	v_cvt_pk_bf16_f32 v40, v52, v54
	s_waitcnt lgkmcnt(0)
	v_cvt_pk_bf16_f32 v41, v56, v58
	global_store_dwordx4 v[42:43], v[38:41], off nt
	v_lshl_add_u64 v[42:43], v[12:13], 0, s[14:15]
	s_nop 0
	v_cvt_pk_bf16_f32 v38, v45, v47
	v_cvt_pk_bf16_f32 v39, v49, v51
	v_cvt_pk_bf16_f32 v40, v53, v55
	v_cvt_pk_bf16_f32 v41, v57, v59
	ds_read2_b32 v[44:45], v22 offset0:32 offset1:40
	ds_read2_b32 v[46:47], v30 offset0:33 offset1:41
	ds_read2_b32 v[48:49], v31 offset0:34 offset1:42
	ds_read2_b32 v[50:51], v32 offset0:35 offset1:43
	ds_read2_b32 v[52:53], v33 offset0:36 offset1:44
	ds_read2_b32 v[54:55], v34 offset0:37 offset1:45
	ds_read2_b32 v[56:57], v35 offset0:38 offset1:46
	ds_read2_b32 v[58:59], v36 offset0:39 offset1:47
	global_store_dwordx4 v[42:43], v[38:41], off nt
	v_lshl_add_u64 v[42:43], v[14:15], 0, s[14:15]
	s_waitcnt lgkmcnt(6)
	v_cvt_pk_bf16_f32 v38, v44, v46
	s_waitcnt lgkmcnt(4)
	v_cvt_pk_bf16_f32 v39, v48, v50
	s_waitcnt lgkmcnt(2)
	v_cvt_pk_bf16_f32 v40, v52, v54
	s_waitcnt lgkmcnt(0)
	v_cvt_pk_bf16_f32 v41, v56, v58
	global_store_dwordx4 v[42:43], v[38:41], off nt
	v_lshl_add_u64 v[42:43], v[16:17], 0, s[14:15]
	s_nop 0
	v_cvt_pk_bf16_f32 v38, v45, v47
	v_cvt_pk_bf16_f32 v39, v49, v51
	v_cvt_pk_bf16_f32 v40, v53, v55
	v_cvt_pk_bf16_f32 v41, v57, v59
	ds_read2_b32 v[44:45], v22 offset0:48 offset1:56
	ds_read2_b32 v[46:47], v30 offset0:49 offset1:57
	ds_read2_b32 v[48:49], v31 offset0:50 offset1:58
	ds_read2_b32 v[50:51], v32 offset0:51 offset1:59
	ds_read2_b32 v[52:53], v33 offset0:52 offset1:60
	ds_read2_b32 v[54:55], v34 offset0:53 offset1:61
	ds_read2_b32 v[56:57], v35 offset0:54 offset1:62
	ds_read2_b32 v[58:59], v36 offset0:55 offset1:63
	global_store_dwordx4 v[42:43], v[38:41], off nt
	v_lshl_add_u64 v[42:43], v[18:19], 0, s[14:15]
	s_waitcnt lgkmcnt(6)
	v_cvt_pk_bf16_f32 v38, v44, v46
	s_waitcnt lgkmcnt(4)
	v_cvt_pk_bf16_f32 v39, v48, v50
	s_waitcnt lgkmcnt(2)
	v_cvt_pk_bf16_f32 v40, v52, v54
	s_waitcnt lgkmcnt(0)
	v_cvt_pk_bf16_f32 v41, v56, v58
	global_store_dwordx4 v[42:43], v[38:41], off nt
	v_lshl_add_u64 v[42:43], v[20:21], 0, s[14:15]
	s_mov_b64 s[14:15], 0
	v_cvt_pk_bf16_f32 v38, v45, v47
	v_cvt_pk_bf16_f32 v39, v49, v51
	v_cvt_pk_bf16_f32 v40, v53, v55
	v_cvt_pk_bf16_f32 v41, v57, v59
	global_store_dwordx4 v[42:43], v[38:41], off nt
	s_barrier
	s_branch .LBB0_123

; #define LAS __attribute__((address_space(3)))
; template <bool GAIN = false>
; __device__ __forceinline__ void tr_super(const float* W, size_t ldw, int k0, int c0, bf16* WT, int nd0, int K, LAS unsigned char* lds, int wave, int lane, int kd0, const float* gk = nullptr) {
;     LAS float* tile = (LAS float*)lds;
; #pragma unroll
;     for (int r = 0; r < 8; ++r)
; #pragma unroll
;         for (int h = 0; h < 8; ++h) tile[(8 * wave + r) * 513 + 64 * h + lane] = __builtin_nontemporal_load(W + (size_t)(k0 + 8 * wave + r) * ldw + c0 + 64 * h + lane);
;     __syncthreads();
; __device__ __forceinline__ void cv_tail_w2(const float* W, bf16* WT, unsigned* head, LAS unsigned char* lds, int wave, int lane) {
;     ...
;     volatile LAS unsigned* slot = (volatile LAS unsigned*)(lds + 139264);
;     for (;;) {
;         if (wave == 0 && lane == 0) *slot = __hip_atomic_fetch_add(head, 1u, __ATOMIC_RELAXED, __HIP_MEMORY_SCOPE_AGENT);
;         __syncthreads();
;         const unsigned o = (unsigned)__builtin_amdgcn_readfirstlane((int)*slot);
;         if (o >= (unsigned)N) break;
;         tr_super(W, D, 64 * (int)(o >> 3), 512 * (int)(o & 7), WT, 512 * (int)(o & 7), FF, lds, wave, lane, 64 * (int)(o >> 3));
.LBB0_853:
	s_or_b64 exec, exec, s[12:13]
	s_waitcnt lgkmcnt(0)
	s_barrier
	ds_read_b32 v37, v2
	s_mov_b64 s[12:13], -1
	s_waitcnt lgkmcnt(0)
	v_readfirstlane_b32 s14, v37
	s_cmpk_gt_u32 s14, 0x55f
	s_cbranch_scc1 .LBB0_848
	s_lshl_b32 s10, s14, 9
	s_and_b32 s15, s10, 0xe00
	s_and_b32 s10, s14, 0x7f8
	s_add_i32 s10, s10, s61
	s_lshl_b32 s12, s10, 3
	s_lshl_b32 s10, s15, 2
	s_mov_b32 s13, s11
	v_lshl_add_u64 v[38:39], v[4:5], 0, s[10:11]
	s_lshl_b64 s[16:17], s[12:13], 14
	s_or_b32 s10, s12, 1
	v_lshl_add_u64 v[40:41], v[38:39], 0, s[16:17]
	s_lshl_b64 s[16:17], s[10:11], 14
	s_or_b32 s10, s12, 2
	global_load_dword v37, v[40:41], off nt
	global_load_dword v42, v[40:41], off offset:256 nt
	global_load_dword v43, v[40:41], off offset:512 nt
	global_load_dword v44, v[40:41], off offset:768 nt
	global_load_dword v45, v[40:41], off offset:1024 nt
	global_load_dword v46, v[40:41], off offset:1280 nt
	global_load_dword v47, v[40:41], off offset:1536 nt
	global_load_dword v48, v[40:41], off offset:1792 nt
	v_lshl_add_u64 v[40:41], v[38:39], 0, s[16:17]
	s_lshl_b64 s[16:17], s[10:11], 14
	s_or_b32 s10, s12, 3
	global_load_dword v49, v[40:41], off nt
	global_load_dword v50, v[40:41], off offset:256 nt
	global_load_dword v51, v[40:41], off offset:512 nt
	global_load_dword v52, v[40:41], off offset:768 nt
	global_load_dword v53, v[40:41], off offset:1024 nt
	global_load_dword v54, v[40:41], off offset:1280 nt
	global_load_dword v55, v[40:41], off offset:1536 nt
	global_load_dword v56, v[40:41], off offset:1792 nt
	v_lshl_add_u64 v[40:41], v[38:39], 0, s[16:17]
	s_lshl_b64 s[16:17], s[10:11], 14
	s_or_b32 s10, s12, 4
	global_load_dword v57, v[40:41], off nt
	global_load_dword v58, v[40:41], off offset:256 nt
	global_load_dword v59, v[40:41], off offset:512 nt
	global_load_dword v60, v[40:41], off offset:768 nt
	global_load_dword v61, v[40:41], off offset:1024 nt
	global_load_dword v62, v[40:41], off offset:1280 nt
	global_load_dword v63, v[40:41], off offset:1536 nt
	global_load_dword v64, v[40:41], off offset:1792 nt
	v_lshl_add_u64 v[40:41], v[38:39], 0, s[16:17]
	s_lshl_b64 s[16:17], s[10:11], 14
	s_or_b32 s10, s12, 5
	global_load_dword v65, v[40:41], off nt
	global_load_dword v66, v[40:41], off offset:256 nt
	global_load_dword v67, v[40:41], off offset:512 nt
	global_load_dword v68, v[40:41], off offset:768 nt
	global_load_dword v69, v[40:41], off offset:1024 nt
	global_load_dword v70, v[40:41], off offset:1280 nt
	global_load_dword v71, v[40:41], off offset:1536 nt
	global_load_dword v72, v[40:41], off offset:1792 nt
	v_lshl_add_u64 v[40:41], v[38:39], 0, s[16:17]
	s_lshl_b64 s[16:17], s[10:11], 14
	s_or_b32 s10, s12, 6
	global_load_dword v73, v[40:41], off nt
	global_load_dword v74, v[40:41], off offset:256 nt
	global_load_dword v75, v[40:41], off offset:512 nt
	global_load_dword v76, v[40:41], off offset:768 nt
	global_load_dword v77, v[40:41], off offset:1024 nt
	global_load_dword v78, v[40:41], off offset:1280 nt
	global_load_dword v79, v[40:41], off offset:1536 nt
	global_load_dword v80, v[40:41], off offset:1792 nt
	v_lshl_add_u64 v[40:41], v[38:39], 0, s[16:17]
	s_lshl_b64 s[16:17], s[10:11], 14
	s_or_b32 s10, s12, 7
	s_lshl_b64 s[12:13], s[10:11], 14
	global_load_dword v81, v[40:41], off nt
	global_load_dword v82, v[40:41], off offset:256 nt
	global_load_dword v83, v[40:41], off offset:512 nt
	global_load_dword v84, v[40:41], off offset:768 nt
	global_load_dword v85, v[40:41], off offset:1024 nt
	global_load_dword v86, v[40:41], off offset:1280 nt
	global_load_dword v87, v[40:41], off offset:1536 nt
	global_load_dword v88, v[40:41], off offset:1792 nt
	v_lshl_add_u64 v[40:41], v[38:39], 0, s[16:17]
	v_lshl_add_u64 v[38:39], v[38:39], 0, s[12:13]
	global_load_dword v89, v[40:41], off nt
	global_load_dword v90, v[40:41], off offset:256 nt
	global_load_dword v91, v[40:41], off offset:512 nt
	global_load_dword v92, v[40:41], off offset:768 nt
	global_load_dword v93, v[40:41], off offset:1024 nt
	global_load_dword v94, v[40:41], off offset:1280 nt
	global_load_dword v95, v[40:41], off offset:1536 nt
	global_load_dword v96, v[40:41], off offset:1792 nt
	s_nop 0
	global_load_dword v40, v[38:39], off nt
	global_load_dword v41, v[38:39], off offset:256 nt
	global_load_dword v97, v[38:39], off offset:512 nt
	global_load_dword v98, v[38:39], off offset:768 nt
	global_load_dword v99, v[38:39], off offset:1024 nt
	global_load_dword v100, v[38:39], off offset:1280 nt
	global_load_dword v101, v[38:39], off offset:1536 nt
	global_load_dword v102, v[38:39], off offset:1792 nt
	s_add_i32 s15, s15, s3
	s_ashr_i32 s12, s15, 8
	s_lshr_b32 s10, s14, 3
	s_mulk_i32 s12, 0xac
	s_add_i32 s12, s12, s10
	s_ashr_i32 s13, s12, 31
	s_lshl_b64 s[12:13], s[12:13], 15
	s_waitcnt vmcnt(62)
	ds_write2st64_b32 v1, v37, v42 offset1:1
	s_waitcnt vmcnt(60)
	ds_write2st64_b32 v1, v43, v44 offset0:2 offset1:3
	s_waitcnt vmcnt(58)
	ds_write2st64_b32 v1, v45, v46 offset0:4 offset1:5
	s_waitcnt vmcnt(56)
	ds_write2st64_b32 v1, v47, v48 offset0:6 offset1:7
	s_waitcnt vmcnt(54)
	ds_write2st64_b32 v23, v49, v50 offset0:8 offset1:9
	s_waitcnt vmcnt(52)
	ds_write2st64_b32 v23, v51, v52 offset0:10 offset1:11
	s_waitcnt vmcnt(50)
	ds_write2st64_b32 v23, v53, v54 offset0:12 offset1:13
	s_waitcnt vmcnt(48)
	ds_write2st64_b32 v23, v55, v56 offset0:14 offset1:15
	s_waitcnt vmcnt(46)
	ds_write2st64_b32 v24, v57, v58 offset0:16 offset1:17
	s_waitcnt vmcnt(44)
	ds_write2st64_b32 v24, v59, v60 offset0:18 offset1:19
	s_waitcnt vmcnt(42)
; #define LAS __attribute__((address_space(3)))
; __host__ __device__ __forceinline__ size_t blk(int r, int k, int K) { return (((size_t)((r >> 8) * (K >> 6) + (k >> 6))) << 14) + (size_t)(((r & 255) << 6) + (k & 63)); }
; __device__ __forceinline__ unsigned pk2(float lo, float hi) { f32x2 v = {lo, hi}; bf16x2_t b = __builtin_convertvector(v, bf16x2_t); return __builtin_bit_cast(unsigned, b); }
; template <bool GAIN = false>
; __device__ __forceinline__ void tr_super(const float* W, size_t ldw, int k0, int c0, bf16* WT, int nd0, int K, LAS unsigned char* lds, int wave, int lane, int kd0, const float* gk = nullptr) {
;     ...
;     const int c = lane & 7;
;     f32x4 g0 = {1.f, 1.f, 1.f, 1.f}, g1 = g0;
;     if (GAIN) { g0 = *(const f32x4*)(gk + k0 + 8 * c); g1 = *(const f32x4*)(gk + k0 + 8 * c + 4); }
; #pragma unroll
;     for (int j = 0; j < 8; ++j) { const int n = (lane >> 3) + 8 * j; const LAS float* t = tile + (8 * c) * 513 + 64 * wave + n;
;         u32x4 o; o.x = pk2(t[0 * 513] * g0.x, t[1 * 513] * g0.y); o.y = pk2(t[2 * 513] * g0.z, t[3 * 513] * g0.w); o.z = pk2(t[4 * 513] * g1.x, t[5 * 513] * g1.y); o.w = pk2(t[6 * 513] * g1.z, t[7 * 513] * g1.w);
;         *(u32x4*)(WT + blk(nd0 + 64 * wave + n, kd0 + 8 * c, K)) = o; }
;     __syncthreads();
	ds_write2st64_b32 v24, v61, v62 offset0:20 offset1:21
	s_waitcnt vmcnt(40)
	ds_write2st64_b32 v24, v63, v64 offset0:22 offset1:23
	s_waitcnt vmcnt(38)
	ds_write2st64_b32 v25, v65, v66 offset0:24 offset1:25
	s_waitcnt vmcnt(36)
	ds_write2st64_b32 v25, v67, v68 offset0:26 offset1:27
	s_waitcnt vmcnt(34)
	ds_write2st64_b32 v25, v69, v70 offset0:28 offset1:29
	s_waitcnt vmcnt(32)
	ds_write2st64_b32 v25, v71, v72 offset0:30 offset1:31
	s_waitcnt vmcnt(30)
	ds_write2st64_b32 v26, v73, v74 offset0:32 offset1:33
	s_waitcnt vmcnt(28)
	ds_write2st64_b32 v26, v75, v76 offset0:34 offset1:35
	s_waitcnt vmcnt(26)
	ds_write2st64_b32 v26, v77, v78 offset0:36 offset1:37
	s_waitcnt vmcnt(24)
	ds_write2st64_b32 v26, v79, v80 offset0:38 offset1:39
	s_waitcnt vmcnt(22)
	ds_write2st64_b32 v27, v81, v82 offset0:40 offset1:41
	s_waitcnt vmcnt(20)
	ds_write2st64_b32 v27, v83, v84 offset0:42 offset1:43
	s_waitcnt vmcnt(18)
	ds_write2st64_b32 v27, v85, v86 offset0:44 offset1:45
	s_waitcnt vmcnt(16)
	ds_write2st64_b32 v27, v87, v88 offset0:46 offset1:47
	s_waitcnt vmcnt(14)
	ds_write2st64_b32 v28, v89, v90 offset0:48 offset1:49
	s_waitcnt vmcnt(12)
	ds_write2st64_b32 v28, v91, v92 offset0:50 offset1:51
	s_waitcnt vmcnt(10)
	ds_write2st64_b32 v28, v93, v94 offset0:52 offset1:53
	s_waitcnt vmcnt(8)
	ds_write2st64_b32 v28, v95, v96 offset0:54 offset1:55
	s_waitcnt vmcnt(6)
	ds_write2st64_b32 v29, v40, v41 offset0:56 offset1:57
	s_waitcnt vmcnt(4)
	ds_write2st64_b32 v29, v97, v98 offset0:58 offset1:59
	s_waitcnt vmcnt(2)
	ds_write2st64_b32 v29, v99, v100 offset0:60 offset1:61
	s_waitcnt vmcnt(0)
	ds_write2st64_b32 v29, v101, v102 offset0:62 offset1:63
	s_waitcnt lgkmcnt(0)
	s_barrier
	ds_read2_b32 v[42:43], v30 offset0:1 offset1:9
	ds_read2_b32 v[44:45], v22 offset1:8
	ds_read2_b32 v[46:47], v31 offset0:2 offset1:10
	ds_read2_b32 v[48:49], v32 offset0:3 offset1:11
	ds_read2_b32 v[50:51], v33 offset0:4 offset1:12
	ds_read2_b32 v[52:53], v34 offset0:5 offset1:13
	ds_read2_b32 v[54:55], v35 offset0:6 offset1:14
	ds_read2_b32 v[56:57], v36 offset0:7 offset1:15
	s_waitcnt lgkmcnt(6)
	v_cvt_pk_bf16_f32 v38, v44, v42
	s_waitcnt lgkmcnt(4)
	v_cvt_pk_bf16_f32 v39, v46, v48
	s_waitcnt lgkmcnt(2)
	v_cvt_pk_bf16_f32 v40, v50, v52
	v_lshl_add_u64 v[58:59], v[6:7], 0, s[12:13]
	s_waitcnt lgkmcnt(0)
	v_cvt_pk_bf16_f32 v41, v54, v56
	global_store_dwordx4 v[58:59], v[38:41], off nt
	s_nop 1
	v_cvt_pk_bf16_f32 v38, v45, v43
	v_cvt_pk_bf16_f32 v39, v47, v49
	v_cvt_pk_bf16_f32 v40, v51, v53
	v_cvt_pk_bf16_f32 v41, v55, v57
	ds_read2_b32 v[44:45], v22 offset0:16 offset1:24
	ds_read2_b32 v[46:47], v30 offset0:17 offset1:25
	ds_read2_b32 v[48:49], v31 offset0:18 offset1:26
	ds_read2_b32 v[50:51], v32 offset0:19 offset1:27
	ds_read2_b32 v[52:53], v33 offset0:20 offset1:28
	ds_read2_b32 v[54:55], v34 offset0:21 offset1:29
	ds_read2_b32 v[56:57], v35 offset0:22 offset1:30
	ds_read2_b32 v[58:59], v36 offset0:23 offset1:31
	v_lshl_add_u64 v[42:43], v[8:9], 0, s[12:13]
	global_store_dwordx4 v[42:43], v[38:41], off nt
	v_lshl_add_u64 v[42:43], v[10:11], 0, s[12:13]
	s_waitcnt lgkmcnt(6)
	v_cvt_pk_bf16_f32 v38, v44, v46
	s_waitcnt lgkmcnt(4)
	v_cvt_pk_bf16_f32 v39, v48, v50
	s_waitcnt lgkmcnt(2)
	v_cvt_pk_bf16_f32 v40, v52, v54
	s_waitcnt lgkmcnt(0)
	v_cvt_pk_bf16_f32 v41, v56, v58
	global_store_dwordx4 v[42:43], v[38:41], off nt
	v_lshl_add_u64 v[42:43], v[12:13], 0, s[12:13]
	s_nop 0
	v_cvt_pk_bf16_f32 v38, v45, v47
	v_cvt_pk_bf16_f32 v39, v49, v51
	v_cvt_pk_bf16_f32 v40, v53, v55
	v_cvt_pk_bf16_f32 v41, v57, v59
	ds_read2_b32 v[44:45], v22 offset0:32 offset1:40
	ds_read2_b32 v[46:47], v30 offset0:33 offset1:41
	ds_read2_b32 v[48:49], v31 offset0:34 offset1:42
	ds_read2_b32 v[50:51], v32 offset0:35 offset1:43
	ds_read2_b32 v[52:53], v33 offset0:36 offset1:44
	ds_read2_b32 v[54:55], v34 offset0:37 offset1:45
	ds_read2_b32 v[56:57], v35 offset0:38 offset1:46
	ds_read2_b32 v[58:59], v36 offset0:39 offset1:47
	global_store_dwordx4 v[42:43], v[38:41], off nt
	v_lshl_add_u64 v[42:43], v[14:15], 0, s[12:13]
	s_waitcnt lgkmcnt(6)
	v_cvt_pk_bf16_f32 v38, v44, v46
	s_waitcnt lgkmcnt(4)
	v_cvt_pk_bf16_f32 v39, v48, v50
	s_waitcnt lgkmcnt(2)
	v_cvt_pk_bf16_f32 v40, v52, v54
	s_waitcnt lgkmcnt(0)
	v_cvt_pk_bf16_f32 v41, v56, v58
	global_store_dwordx4 v[42:43], v[38:41], off nt
	v_lshl_add_u64 v[42:43], v[16:17], 0, s[12:13]
	s_nop 0
	v_cvt_pk_bf16_f32 v38, v45, v47
	v_cvt_pk_bf16_f32 v39, v49, v51
	v_cvt_pk_bf16_f32 v40, v53, v55
	v_cvt_pk_bf16_f32 v41, v57, v59
	ds_read2_b32 v[44:45], v22 offset0:48 offset1:56
	ds_read2_b32 v[46:47], v30 offset0:49 offset1:57
	ds_read2_b32 v[48:49], v31 offset0:50 offset1:58
	ds_read2_b32 v[50:51], v32 offset0:51 offset1:59
	ds_read2_b32 v[52:53], v33 offset0:52 offset1:60
	ds_read2_b32 v[54:55], v34 offset0:53 offset1:61
	ds_read2_b32 v[56:57], v35 offset0:54 offset1:62
	ds_read2_b32 v[58:59], v36 offset0:55 offset1:63
	global_store_dwordx4 v[42:43], v[38:41], off nt
	v_lshl_add_u64 v[42:43], v[18:19], 0, s[12:13]
	s_waitcnt lgkmcnt(6)
	v_cvt_pk_bf16_f32 v38, v44, v46
	s_waitcnt lgkmcnt(4)
	v_cvt_pk_bf16_f32 v39, v48, v50
	s_waitcnt lgkmcnt(2)
	v_cvt_pk_bf16_f32 v40, v52, v54
	s_waitcnt lgkmcnt(0)
	v_cvt_pk_bf16_f32 v41, v56, v58
	global_store_dwordx4 v[42:43], v[38:41], off nt
	v_lshl_add_u64 v[42:43], v[20:21], 0, s[12:13]
	s_mov_b64 s[12:13], 0
	v_cvt_pk_bf16_f32 v38, v45, v47
	v_cvt_pk_bf16_f32 v39, v49, v51
	v_cvt_pk_bf16_f32 v40, v53, v55
	v_cvt_pk_bf16_f32 v41, v57, v59
	global_store_dwordx4 v[42:43], v[38:41], off nt
	s_barrier
	s_branch .LBB0_848

;     __device__ __forceinline__ void fused(f32x4 (&acc)[2][2][4][2], const Unit& u, int wr, int wc, int fr, int fq, PG8_LAS unsigned char* lds, int wid, int lane) const {
;     ...
; #pragma unroll
;         for (int ai = 0; ai < 2; ++ai)
; #pragma unroll
;             for (int m = 0; m < 4; ++m) { const int lr = ai * HALF + wr * 64 + m * 16 + fr; const float rs = bad ? qnan : St[lr]; const size_t off = (size_t)(u.pm * BM + lr) * D + col0;
; #pragma unroll
;                 for (int bj = 0; bj < 2; ++bj) { const f32x4 g0 = *(const f32x4*)(gain + col0 + bj * HALF), g1 = *(const f32x4*)(gain + col0 + bj * HALF + 4);
;                     *(f32x4*)(out + off + bj * HALF) = acc[ai][bj][m][0] * rs * g0; *(f32x4*)(out + off + bj * HALF + 4) = acc[ai][bj][m][1] * rs * g1; }
;                 asm volatile("" ::: "memory"); }
.LBB0_977:
	global_load_dwordx4 v[162:165], v[140:141], off
	global_load_dwordx4 v[196:199], v[140:141], off offset:16
	v_mov_b32_e32 v157, v139
	s_waitcnt lgkmcnt(0)
	v_pk_mul_f32 v[128:129], v[128:129], v[160:161] op_sel_hi:[1,0]
	v_pk_mul_f32 v[126:127], v[126:127], v[160:161] op_sel_hi:[1,0]
	v_pk_mul_f32 v[202:203], v[122:123], v[160:161] op_sel_hi:[1,0]
	v_lshlrev_b64 v[122:123], 14, v[156:157]
	v_pk_mul_f32 v[200:201], v[124:125], v[160:161] op_sel_hi:[1,0]
	v_lshl_add_u64 v[156:157], v[142:143], 0, v[122:123]
	v_pk_mul_f32 v[120:121], v[120:121], v[160:161] op_sel_hi:[1,0]
	v_pk_mul_f32 v[118:119], v[118:119], v[160:161] op_sel_hi:[1,0]
	s_andn2_b64 vcc, exec, s[8:9]
	s_waitcnt vmcnt(1)
	v_pk_mul_f32 v[124:125], v[164:165], v[128:129]
	v_pk_mul_f32 v[122:123], v[162:163], v[126:127]
	s_waitcnt vmcnt(0)
	v_pk_mul_f32 v[128:129], v[198:199], v[200:201]
	v_pk_mul_f32 v[126:127], v[196:197], v[202:203]
	global_store_dwordx4 v[156:157], v[122:125], off nt
	global_store_dwordx4 v[156:157], v[126:129], off offset:16 nt
	global_load_dwordx4 v[122:125], v[140:141], off offset:512
	s_nop 0
	global_load_dwordx4 v[126:129], v[140:141], off offset:528
	v_pk_mul_f32 v[162:163], v[116:117], v[160:161] op_sel_hi:[1,0]
	v_pk_mul_f32 v[160:161], v[114:115], v[160:161] op_sel_hi:[1,0]
	v_cndmask_b32_e64 v114, 0, 1, s[8:9]
	v_cmp_ne_u32_e64 s[6:7], 1, v114
	s_waitcnt vmcnt(1)
	v_pk_mul_f32 v[116:117], v[120:121], v[124:125]
	v_pk_mul_f32 v[114:115], v[118:119], v[122:123]
	s_waitcnt vmcnt(0)
	v_pk_mul_f32 v[120:121], v[162:163], v[128:129]
	v_pk_mul_f32 v[118:119], v[160:161], v[126:127]
	global_store_dwordx4 v[156:157], v[114:117], off offset:512 nt
	global_store_dwordx4 v[156:157], v[118:121], off offset:528 nt
	s_cbranch_vccnz .LBB0_979
	ds_read_b32 v158, v179
.LBB0_979:
	global_load_dwordx4 v[114:117], v[140:141], off
	global_load_dwordx4 v[118:121], v[140:141], off offset:16
	v_add_u32_e32 v122, s56, v170
	v_mov_b32_e32 v123, v139
	s_waitcnt lgkmcnt(0)
	v_pk_mul_f32 v[112:113], v[112:113], v[158:159] op_sel_hi:[1,0]
	v_pk_mul_f32 v[110:111], v[110:111], v[158:159] op_sel_hi:[1,0]
	v_pk_mul_f32 v[126:127], v[106:107], v[158:159] op_sel_hi:[1,0]
	v_lshlrev_b64 v[106:107], 14, v[122:123]
	v_pk_mul_f32 v[124:125], v[108:109], v[158:159] op_sel_hi:[1,0]
	v_lshl_add_u64 v[122:123], v[142:143], 0, v[106:107]
	v_pk_mul_f32 v[104:105], v[104:105], v[158:159] op_sel_hi:[1,0]
	v_pk_mul_f32 v[102:103], v[102:103], v[158:159] op_sel_hi:[1,0]
	s_and_b64 vcc, exec, s[6:7]
	s_waitcnt vmcnt(1)
	v_pk_mul_f32 v[108:109], v[116:117], v[112:113]
	v_pk_mul_f32 v[106:107], v[114:115], v[110:111]
	s_waitcnt vmcnt(0)
	v_pk_mul_f32 v[112:113], v[120:121], v[124:125]
	v_pk_mul_f32 v[110:111], v[118:119], v[126:127]
	global_store_dwordx4 v[122:123], v[106:109], off nt
	global_store_dwordx4 v[122:123], v[110:113], off offset:16 nt
	global_load_dwordx4 v[106:109], v[140:141], off offset:512
	s_nop 0
	global_load_dwordx4 v[110:113], v[140:141], off offset:528
	v_pk_mul_f32 v[114:115], v[100:101], v[158:159] op_sel_hi:[1,0]
	v_pk_mul_f32 v[116:117], v[98:99], v[158:159] op_sel_hi:[1,0]
	s_waitcnt vmcnt(1)
	v_pk_mul_f32 v[100:101], v[104:105], v[108:109]
	v_pk_mul_f32 v[98:99], v[102:103], v[106:107]
	s_waitcnt vmcnt(0)
	v_pk_mul_f32 v[104:105], v[114:115], v[112:113]
	v_pk_mul_f32 v[102:103], v[116:117], v[110:111]
	global_store_dwordx4 v[122:123], v[98:101], off offset:512 nt
	global_store_dwordx4 v[122:123], v[102:105], off offset:528 nt
	s_nop 0
	v_mov_b32_e32 v98, 0x7fc00000
	v_mov_b32_e32 v100, 0x7fc00000
	s_cbranch_vccnz .LBB0_981
	ds_read_b32 v100, v180
.LBB0_981:
	global_load_dwordx4 v[102:105], v[140:141], off
	global_load_dwordx4 v[106:109], v[140:141], off offset:16
	v_add_u32_e32 v110, s56, v171
	v_mov_b32_e32 v111, v139
	s_waitcnt lgkmcnt(0)
	v_pk_mul_f32 v[96:97], v[96:97], v[100:101] op_sel_hi:[1,0]
	v_pk_mul_f32 v[94:95], v[94:95], v[100:101] op_sel_hi:[1,0]
	v_pk_mul_f32 v[114:115], v[90:91], v[100:101] op_sel_hi:[1,0]
	v_lshlrev_b64 v[90:91], 14, v[110:111]
	v_pk_mul_f32 v[112:113], v[92:93], v[100:101] op_sel_hi:[1,0]
	v_lshl_add_u64 v[110:111], v[142:143], 0, v[90:91]
	v_pk_mul_f32 v[88:89], v[88:89], v[100:101] op_sel_hi:[1,0]
	v_pk_mul_f32 v[86:87], v[86:87], v[100:101] op_sel_hi:[1,0]
	s_and_b64 vcc, exec, s[6:7]
	s_waitcnt vmcnt(1)
	v_pk_mul_f32 v[92:93], v[104:105], v[96:97]
	v_pk_mul_f32 v[90:91], v[102:103], v[94:95]
	s_waitcnt vmcnt(0)
	v_pk_mul_f32 v[96:97], v[108:109], v[112:113]
	v_pk_mul_f32 v[94:95], v[106:107], v[114:115]
	global_store_dwordx4 v[110:111], v[90:93], off nt
	global_store_dwordx4 v[110:111], v[94:97], off offset:16 nt
	global_load_dwordx4 v[90:93], v[140:141], off offset:512
	s_nop 0
	global_load_dwordx4 v[94:97], v[140:141], off offset:528
	v_pk_mul_f32 v[102:103], v[84:85], v[100:101] op_sel_hi:[1,0]
	v_pk_mul_f32 v[100:101], v[82:83], v[100:101] op_sel_hi:[1,0]
	s_waitcnt vmcnt(1)
	v_pk_mul_f32 v[84:85], v[88:89], v[92:93]
	v_pk_mul_f32 v[82:83], v[86:87], v[90:91]
	s_waitcnt vmcnt(0)
	v_pk_mul_f32 v[88:89], v[102:103], v[96:97]
	v_pk_mul_f32 v[86:87], v[100:101], v[94:95]
	global_store_dwordx4 v[110:111], v[82:85], off offset:512 nt
	global_store_dwordx4 v[110:111], v[86:89], off offset:528 nt
	s_cbranch_vccnz .LBB0_983
	ds_read_b32 v98, v181
;     __device__ __forceinline__ void fused(f32x4 (&acc)[2][2][4][2], const Unit& u, int wr, int wc, int fr, int fq, PG8_LAS unsigned char* lds, int wid, int lane) const {
;     ...
; #pragma unroll
;         for (int ai = 0; ai < 2; ++ai)
; #pragma unroll
;             for (int m = 0; m < 4; ++m) { const int lr = ai * HALF + wr * 64 + m * 16 + fr; const float rs = bad ? qnan : St[lr]; const size_t off = (size_t)(u.pm * BM + lr) * D + col0;
; #pragma unroll
;                 for (int bj = 0; bj < 2; ++bj) { const f32x4 g0 = *(const f32x4*)(gain + col0 + bj * HALF), g1 = *(const f32x4*)(gain + col0 + bj * HALF + 4);
;                     *(f32x4*)(out + off + bj * HALF) = acc[ai][bj][m][0] * rs * g0; *(f32x4*)(out + off + bj * HALF + 4) = acc[ai][bj][m][1] * rs * g1; }
;                 asm volatile("" ::: "memory"); }
.LBB0_983:
	global_load_dwordx4 v[82:85], v[140:141], off
	global_load_dwordx4 v[86:89], v[140:141], off offset:16
	v_add_u32_e32 v90, s56, v172
	v_mov_b32_e32 v91, v139
	s_waitcnt lgkmcnt(0)
	v_pk_mul_f32 v[80:81], v[80:81], v[98:99] op_sel_hi:[1,0]
	v_pk_mul_f32 v[78:79], v[78:79], v[98:99] op_sel_hi:[1,0]
	v_pk_mul_f32 v[94:95], v[74:75], v[98:99] op_sel_hi:[1,0]
	v_lshlrev_b64 v[74:75], 14, v[90:91]
	v_pk_mul_f32 v[92:93], v[76:77], v[98:99] op_sel_hi:[1,0]
	v_lshl_add_u64 v[90:91], v[142:143], 0, v[74:75]
	v_pk_mul_f32 v[72:73], v[72:73], v[98:99] op_sel_hi:[1,0]
	v_pk_mul_f32 v[70:71], v[70:71], v[98:99] op_sel_hi:[1,0]
	s_and_b64 vcc, exec, s[6:7]
	s_waitcnt vmcnt(1)
	v_pk_mul_f32 v[76:77], v[84:85], v[80:81]
	v_pk_mul_f32 v[74:75], v[82:83], v[78:79]
	s_waitcnt vmcnt(0)
	v_pk_mul_f32 v[80:81], v[88:89], v[92:93]
	v_pk_mul_f32 v[78:79], v[86:87], v[94:95]
	global_store_dwordx4 v[90:91], v[74:77], off nt
	global_store_dwordx4 v[90:91], v[78:81], off offset:16 nt
	global_load_dwordx4 v[74:77], v[140:141], off offset:512
	s_nop 0
	global_load_dwordx4 v[78:81], v[140:141], off offset:528
	v_pk_mul_f32 v[82:83], v[68:69], v[98:99] op_sel_hi:[1,0]
	v_pk_mul_f32 v[84:85], v[66:67], v[98:99] op_sel_hi:[1,0]
	s_waitcnt vmcnt(1)
	v_pk_mul_f32 v[68:69], v[72:73], v[76:77]
	v_pk_mul_f32 v[66:67], v[70:71], v[74:75]
	s_waitcnt vmcnt(0)
	v_pk_mul_f32 v[72:73], v[82:83], v[80:81]
	v_pk_mul_f32 v[70:71], v[84:85], v[78:79]
	global_store_dwordx4 v[90:91], v[66:69], off offset:512 nt
	global_store_dwordx4 v[90:91], v[70:73], off offset:528 nt
	s_nop 0
	v_mov_b32_e32 v66, 0x7fc00000
	v_mov_b32_e32 v68, 0x7fc00000
	s_cbranch_vccnz .LBB0_985
	ds_read_b32 v68, v182
.LBB0_985:
	global_load_dwordx4 v[70:73], v[140:141], off
	global_load_dwordx4 v[74:77], v[140:141], off offset:16
	v_add_u32_e32 v78, s56, v168
	v_mov_b32_e32 v79, v139
	s_waitcnt lgkmcnt(0)
	v_pk_mul_f32 v[64:65], v[64:65], v[68:69] op_sel_hi:[1,0]
	v_pk_mul_f32 v[62:63], v[62:63], v[68:69] op_sel_hi:[1,0]
	v_pk_mul_f32 v[82:83], v[58:59], v[68:69] op_sel_hi:[1,0]
	v_lshlrev_b64 v[58:59], 14, v[78:79]
	v_pk_mul_f32 v[80:81], v[60:61], v[68:69] op_sel_hi:[1,0]
	v_lshl_add_u64 v[78:79], v[142:143], 0, v[58:59]
	v_pk_mul_f32 v[56:57], v[56:57], v[68:69] op_sel_hi:[1,0]
	v_pk_mul_f32 v[54:55], v[54:55], v[68:69] op_sel_hi:[1,0]
	s_and_b64 vcc, exec, s[6:7]
	s_waitcnt vmcnt(1)
	v_pk_mul_f32 v[60:61], v[72:73], v[64:65]
	v_pk_mul_f32 v[58:59], v[70:71], v[62:63]
	s_waitcnt vmcnt(0)
	v_pk_mul_f32 v[64:65], v[76:77], v[80:81]
	v_pk_mul_f32 v[62:63], v[74:75], v[82:83]
	global_store_dwordx4 v[78:79], v[58:61], off nt
	global_store_dwordx4 v[78:79], v[62:65], off offset:16 nt
	global_load_dwordx4 v[58:61], v[140:141], off offset:512
	s_nop 0
	global_load_dwordx4 v[62:65], v[140:141], off offset:528
	v_pk_mul_f32 v[70:71], v[52:53], v[68:69] op_sel_hi:[1,0]
	v_pk_mul_f32 v[68:69], v[50:51], v[68:69] op_sel_hi:[1,0]
	s_waitcnt vmcnt(1)
	v_pk_mul_f32 v[52:53], v[56:57], v[60:61]
	v_pk_mul_f32 v[50:51], v[54:55], v[58:59]
	s_waitcnt vmcnt(0)
	v_pk_mul_f32 v[56:57], v[70:71], v[64:65]
	v_pk_mul_f32 v[54:55], v[68:69], v[62:63]
	global_store_dwordx4 v[78:79], v[50:53], off offset:512 nt
	global_store_dwordx4 v[78:79], v[54:57], off offset:528 nt
	s_cbranch_vccnz .LBB0_987
	ds_read_b32 v66, v183
;     __device__ __forceinline__ void fused(f32x4 (&acc)[2][2][4][2], const Unit& u, int wr, int wc, int fr, int fq, PG8_LAS unsigned char* lds, int wid, int lane) const {
;     ...
; #pragma unroll
;         for (int ai = 0; ai < 2; ++ai)
; #pragma unroll
;             for (int m = 0; m < 4; ++m) { const int lr = ai * HALF + wr * 64 + m * 16 + fr; const float rs = bad ? qnan : St[lr]; const size_t off = (size_t)(u.pm * BM + lr) * D + col0;
; #pragma unroll
;                 for (int bj = 0; bj < 2; ++bj) { const f32x4 g0 = *(const f32x4*)(gain + col0 + bj * HALF), g1 = *(const f32x4*)(gain + col0 + bj * HALF + 4);
;                     *(f32x4*)(out + off + bj * HALF) = acc[ai][bj][m][0] * rs * g0; *(f32x4*)(out + off + bj * HALF + 4) = acc[ai][bj][m][1] * rs * g1; }
;                 asm volatile("" ::: "memory"); }
.LBB0_987:
	global_load_dwordx4 v[50:53], v[140:141], off
	global_load_dwordx4 v[54:57], v[140:141], off offset:16
	v_add_u32_e32 v58, s56, v173
	v_mov_b32_e32 v59, v139
	s_waitcnt lgkmcnt(0)
	v_pk_mul_f32 v[48:49], v[48:49], v[66:67] op_sel_hi:[1,0]
	v_pk_mul_f32 v[46:47], v[46:47], v[66:67] op_sel_hi:[1,0]
	v_pk_mul_f32 v[62:63], v[42:43], v[66:67] op_sel_hi:[1,0]
	v_lshlrev_b64 v[42:43], 14, v[58:59]
	v_pk_mul_f32 v[60:61], v[44:45], v[66:67] op_sel_hi:[1,0]
	v_lshl_add_u64 v[58:59], v[142:143], 0, v[42:43]
	v_pk_mul_f32 v[40:41], v[40:41], v[66:67] op_sel_hi:[1,0]
	v_pk_mul_f32 v[38:39], v[38:39], v[66:67] op_sel_hi:[1,0]
	s_and_b64 vcc, exec, s[6:7]
	s_waitcnt vmcnt(1)
	v_pk_mul_f32 v[44:45], v[52:53], v[48:49]
	v_pk_mul_f32 v[42:43], v[50:51], v[46:47]
	s_waitcnt vmcnt(0)
	v_pk_mul_f32 v[48:49], v[56:57], v[60:61]
	v_pk_mul_f32 v[46:47], v[54:55], v[62:63]
	global_store_dwordx4 v[58:59], v[42:45], off nt
	global_store_dwordx4 v[58:59], v[46:49], off offset:16 nt
	global_load_dwordx4 v[42:45], v[140:141], off offset:512
	s_nop 0
	global_load_dwordx4 v[46:49], v[140:141], off offset:528
	v_pk_mul_f32 v[50:51], v[36:37], v[66:67] op_sel_hi:[1,0]
	v_pk_mul_f32 v[52:53], v[34:35], v[66:67] op_sel_hi:[1,0]
	s_waitcnt vmcnt(1)
	v_pk_mul_f32 v[36:37], v[40:41], v[44:45]
	v_pk_mul_f32 v[34:35], v[38:39], v[42:43]
	s_waitcnt vmcnt(0)
	v_pk_mul_f32 v[40:41], v[50:51], v[48:49]
	v_pk_mul_f32 v[38:39], v[52:53], v[46:47]
	global_store_dwordx4 v[58:59], v[34:37], off offset:512 nt
	global_store_dwordx4 v[58:59], v[38:41], off offset:528 nt
	s_nop 0
	v_mov_b32_e32 v34, 0x7fc00000
	v_mov_b32_e32 v36, 0x7fc00000
	s_cbranch_vccnz .LBB0_989
	ds_read_b32 v36, v184
.LBB0_989:
	global_load_dwordx4 v[38:41], v[140:141], off
	global_load_dwordx4 v[42:45], v[140:141], off offset:16
	v_add_u32_e32 v46, s56, v174
	v_mov_b32_e32 v47, v139
	s_waitcnt lgkmcnt(0)
	v_pk_mul_f32 v[32:33], v[32:33], v[36:37] op_sel_hi:[1,0]
	v_pk_mul_f32 v[30:31], v[30:31], v[36:37] op_sel_hi:[1,0]
	v_pk_mul_f32 v[50:51], v[26:27], v[36:37] op_sel_hi:[1,0]
	v_lshlrev_b64 v[26:27], 14, v[46:47]
	v_pk_mul_f32 v[48:49], v[28:29], v[36:37] op_sel_hi:[1,0]
	v_lshl_add_u64 v[46:47], v[142:143], 0, v[26:27]
	v_pk_mul_f32 v[24:25], v[24:25], v[36:37] op_sel_hi:[1,0]
	v_pk_mul_f32 v[22:23], v[22:23], v[36:37] op_sel_hi:[1,0]
	s_and_b64 vcc, exec, s[6:7]
	s_waitcnt vmcnt(1)
	v_pk_mul_f32 v[28:29], v[40:41], v[32:33]
	v_pk_mul_f32 v[26:27], v[38:39], v[30:31]
	s_waitcnt vmcnt(0)
	v_pk_mul_f32 v[32:33], v[44:45], v[48:49]
	v_pk_mul_f32 v[30:31], v[42:43], v[50:51]
	global_store_dwordx4 v[46:47], v[26:29], off nt
	global_store_dwordx4 v[46:47], v[30:33], off offset:16 nt
	global_load_dwordx4 v[26:29], v[140:141], off offset:512
	s_nop 0
	global_load_dwordx4 v[30:33], v[140:141], off offset:528
	v_pk_mul_f32 v[38:39], v[20:21], v[36:37] op_sel_hi:[1,0]
	v_pk_mul_f32 v[36:37], v[18:19], v[36:37] op_sel_hi:[1,0]
	s_waitcnt vmcnt(1)
	v_pk_mul_f32 v[20:21], v[24:25], v[28:29]
	v_pk_mul_f32 v[18:19], v[22:23], v[26:27]
	s_waitcnt vmcnt(0)
	v_pk_mul_f32 v[24:25], v[38:39], v[32:33]
	v_pk_mul_f32 v[22:23], v[36:37], v[30:31]
	global_store_dwordx4 v[46:47], v[18:21], off offset:512 nt
	global_store_dwordx4 v[46:47], v[22:25], off offset:528 nt
	s_cbranch_vccnz .LBB0_991
	ds_read_b32 v34, v185
.LBB0_991:
	global_load_dwordx4 v[18:21], v[140:141], off
	global_load_dwordx4 v[22:25], v[140:141], off offset:16
	v_add_u32_e32 v26, s56, v175
	v_mov_b32_e32 v27, v139
	s_waitcnt lgkmcnt(0)
	v_pk_mul_f32 v[16:17], v[16:17], v[34:35] op_sel_hi:[1,0]
	v_pk_mul_f32 v[14:15], v[14:15], v[34:35] op_sel_hi:[1,0]
	v_pk_mul_f32 v[30:31], v[10:11], v[34:35] op_sel_hi:[1,0]
	v_lshlrev_b64 v[10:11], 14, v[26:27]
	v_pk_mul_f32 v[28:29], v[12:13], v[34:35] op_sel_hi:[1,0]
	v_lshl_add_u64 v[26:27], v[142:143], 0, v[10:11]
	v_pk_mul_f32 v[8:9], v[8:9], v[34:35] op_sel_hi:[1,0]
	v_pk_mul_f32 v[6:7], v[6:7], v[34:35] op_sel_hi:[1,0]
	s_andn2_b64 vcc, exec, s[42:43]
	s_mov_b64 s[6:7], -1
	s_waitcnt vmcnt(1)
	v_pk_mul_f32 v[12:13], v[20:21], v[16:17]
	v_pk_mul_f32 v[10:11], v[18:19], v[14:15]
	s_waitcnt vmcnt(0)
	v_pk_mul_f32 v[16:17], v[24:25], v[28:29]
	v_pk_mul_f32 v[14:15], v[22:23], v[30:31]
	global_store_dwordx4 v[26:27], v[10:13], off nt
	global_store_dwordx4 v[26:27], v[14:17], off offset:16 nt
	global_load_dwordx4 v[10:13], v[140:141], off offset:512
	s_nop 0
	global_load_dwordx4 v[14:17], v[140:141], off offset:528
	v_pk_mul_f32 v[18:19], v[4:5], v[34:35] op_sel_hi:[1,0]
	v_pk_mul_f32 v[20:21], v[2:3], v[34:35] op_sel_hi:[1,0]
	s_waitcnt vmcnt(1)
	v_pk_mul_f32 v[4:5], v[8:9], v[12:13]
	v_pk_mul_f32 v[2:3], v[6:7], v[10:11]
	s_waitcnt vmcnt(0)
	v_pk_mul_f32 v[8:9], v[18:19], v[16:17]
	v_pk_mul_f32 v[6:7], v[20:21], v[14:15]
	global_store_dwordx4 v[26:27], v[2:5], off offset:512 nt
	global_store_dwordx4 v[26:27], v[6:9], off offset:528 nt
	s_cbranch_vccnz .LBB0_937
	s_andn2_b64 vcc, exec, s[22:23]
	s_cbranch_vccnz .LBB0_936
	s_barrier
	s_branch .LBB0_936
